# IN projection: waves whose weight slab is all zero padding (last N tile, wc 1..3) skip their MFMA runs (less MFMA energy, same results)
# baseline (speedup 1.0000x reference)
;     __host__ __device__ bool next(int i, Unit& u) const { if (i != 0 || S.c >= 2 * (S.nwg - base)) return false; S.unit_of(base + (S.c >> 1), u); u.hm = S.c & 1; return true; }
; template <class Epi, bool ALIGN_EPI, bool SP2, bool BF = false, bool HALFM = false, class Order = StaticOrder>
; __device__ __forceinline__ void gemm_phase(LAS unsigned char* lds, const int tid, const Gemm g, const Order& S, const Epi& E, const bool dry = false) {
;     ...
;         const bool has_next = S.next(ui + 1, nxt);
;         const char* nA = has_next ? (const char*)g.A + (size_t)nxt.pm * tstep + (HALFM ? (size_t)nxt.hm * hstep : (size_t)0) : cA; const char* nB = has_next ? (const char*)g.Bt + (size_t)nxt.pn * tstep : cB;
;     __device__ __forceinline__ void operator()(const f32x4 (&acc)[2][2][4][2], const pg8::Unit& u, int wr, int wc, int fr, int fq) const {
;         const int s = u.pn * 4 + wc;
;         if (s >= 53) return;
.LBB0_560:
	s_lshl_b32 s101, s2, 2
	s_or_b32 s101, s101, s76
	s_cmp_gt_i32 s101, 52
	s_cselect_b32 s101, 1, 0
	s_ashr_i32 s21, s20, 31
	s_lshl_b64 s[8:9], s[20:21], 19
	s_add_u32 s22, s44, s8
	s_addc_u32 s23, s45, s9
	s_and_b64 s[8:9], s[0:1], exec
	s_cselect_b32 s3, s23, s39
	s_cselect_b32 s5, s22, s38
	s_ashr_i32 s19, s18, 31
	s_lshl_b64 s[8:9], s[18:19], 19
	s_add_u32 s24, s29, s8
	s_addc_u32 s25, s41, s9
	s_and_b64 s[8:9], s[0:1], exec
	s_cselect_b32 s8, s25, s37
	s_cselect_b32 s9, s24, s36
	s_add_u32 s11, s36, 0x100
	s_addc_u32 s19, s37, 0
	s_add_u32 s36, s38, 0x40080
	s_addc_u32 s37, s39, 0
	s_cmp_eq_u32 s100, 2
	s_cbranch_scc1 .Lin_w16
	s_waitcnt vmcnt(0)
	s_branch .Lin_wd

; #define PG8_STAGE(bufoff, gbase) do { _Pragma("unroll") for (int _i = 0; _i < 2; ++_i) \
;         __builtin_amdgcn_global_load_lds((const unsigned*)((const char*)(gbase) + voffA[_i]), (LAS unsigned*)(lds + (bufoff) + ldsw + _i * 8192), 16, 0, 0); } while (0)
; #define PG8_LDA(dst, b, h) do { _Pragma("unroll") for (int m = 0; m < 4; ++m) _Pragma("unroll") for (int k = 0; k < 2; ++k) dst[m][k] = *(const LAS h16x8*)(lds + PG8_SA(b, h) + aoff + m * 2048 + k * 1024); } while (0)
; #define PG8_LDB(dst, b, h) do { _Pragma("unroll") for (int n = 0; n < 2; ++n) _Pragma("unroll") for (int k = 0; k < 2; ++k) dst[n][k] = *(const LAS h16x8*)(lds + PG8_SB(b, h) + boff + n * 2048 + k * 1024); } while (0)
; #define PG8_LDA1(dst, b) do { if constexpr (!HALFM) PG8_LDA(dst, b, 1); } while (0)
; #define PG8_MMA1(At, B0, B1) do { if constexpr (!HALFM) { PG8_MMA(1, 0, At, B0); PG8_MMA(1, 1, At, B1); } } while (0)
; #define PG8_WAIT_V(n) asm volatile("s_waitcnt vmcnt(" #n ")" ::: "memory")
; #define PG8_WAIT_L(n) asm volatile("s_waitcnt lgkmcnt(" #n ")" ::: "memory")
; #define PG8_BAR __builtin_amdgcn_s_barrier()
; #define PG8_SCHED __builtin_amdgcn_sched_barrier(0)
; template <class Epi, bool ALIGN_EPI, bool SP2, bool BF = false, bool HALFM = false, class Order = StaticOrder>
; __device__ __forceinline__ void gemm_phase(LAS unsigned char* lds, const int tid, const Gemm g, const Order& S, const Epi& E, const bool dry = false) {
;     ...
;             PG8_LDB(B0, 0, 0); PG8_LDB(B1, 0, 1); PG8_SCHED; PG8_LDA(At, 0, 0); PG8_STAGE(PG8_SA(1, 1), a1 + hstep);
;             PG8_WAIT_V(8); PG8_WAIT_L(0); PG8_BAR; PG8_MMA(0, 0, At, B0); PG8_MMA(0, 1, At, B1); PG8_BAR; PG8_SCHED;
;             PG8_LDA1(At, 0); PG8_STAGE(PG8_SB(0, 0), b2); PG8_STAGE(PG8_SB(0, 1), b2 + hstep); PG8_STAGE(PG8_SA(0, 0), a2);
;             PG8_WAIT_V(8); PG8_WAIT_L(0); PG8_BAR; PG8_MMA1(At, B0, B1); PG8_BAR; PG8_SCHED;
.LBB0_561:
	v_add_u32_e32 v144, s46, v198
	v_add_u32_e32 v160, s49, v198
	ds_read_b128 v[132:135], v144
	ds_read_b128 v[136:139], v144 offset:1024
	ds_read_b128 v[140:143], v144 offset:2048
	ds_read_b128 v[144:147], v144 offset:3072
	ds_read_b128 v[148:151], v160
	ds_read_b128 v[152:155], v160 offset:1024
	ds_read_b128 v[156:159], v160 offset:2048
	ds_read_b128 v[160:163], v160 offset:3072
	s_add_u32 s38, s36, 0xfffc0080
	s_addc_u32 s39, s37, -1
	s_cmp_eq_u32 s21, 12
	s_cselect_b32 s43, s3, s39
	s_cselect_b32 s42, s5, s38
	s_cselect_b32 s39, s8, s19
	s_cselect_b32 s38, s9, s11
	s_nop 0
	s_add_i32 m0, s52, 0xc000
	ds_read_b128 v[170:173], v199
	ds_read_b128 v[174:177], v199 offset:1024
	ds_read_b128 v[178:181], v199 offset:2048
	ds_read_b128 v[182:185], v199 offset:3072
	ds_read_b128 v[186:189], v199 offset:4096
	ds_read_b128 v[190:193], v199 offset:5120
	ds_read_b128 v[200:203], v199 offset:6144
	ds_read_b128 v[204:207], v199 offset:7168
	global_load_lds_dwordx4 v168, s[36:37]
	s_nop 0
	s_add_i32 m0, s52, 0xe000
	s_nop 0
	global_load_lds_dwordx4 v166, s[36:37]
	s_waitcnt vmcnt(8)
	s_waitcnt lgkmcnt(0)
	s_barrier
	s_waitcnt lgkmcnt(0)
	s_cmp_lg_u32 s101, 0
	s_cbranch_scc1 .Lskz_1
	v_mfma_f32_16x16x32_f16 v[70:73], v[132:135], v[170:173], v[70:73]
	v_mfma_f32_16x16x32_f16 v[66:69], v[140:143], v[170:173], v[66:69]
	v_mfma_f32_16x16x32_f16 v[50:53], v[132:135], v[178:181], v[50:53]
	v_mfma_f32_16x16x32_f16 v[46:49], v[140:143], v[178:181], v[46:49]
	v_mfma_f32_16x16x32_f16 v[54:57], v[132:135], v[186:189], v[54:57]
	v_mfma_f32_16x16x32_f16 v[42:45], v[140:143], v[186:189], v[42:45]
	v_mfma_f32_16x16x32_f16 v[38:41], v[132:135], v[200:203], v[38:41]
	v_mfma_f32_16x16x32_f16 v[34:37], v[140:143], v[200:203], v[34:37]
	v_mfma_f32_16x16x32_f16 v[70:73], v[136:139], v[174:177], v[70:73]
	v_mfma_f32_16x16x32_f16 v[66:69], v[144:147], v[174:177], v[66:69]
	v_mfma_f32_16x16x32_f16 v[50:53], v[136:139], v[182:185], v[50:53]
	v_mfma_f32_16x16x32_f16 v[46:49], v[144:147], v[182:185], v[46:49]
	v_mfma_f32_16x16x32_f16 v[54:57], v[136:139], v[190:193], v[54:57]
	v_mfma_f32_16x16x32_f16 v[42:45], v[144:147], v[190:193], v[42:45]
	v_mfma_f32_16x16x32_f16 v[38:41], v[136:139], v[204:207], v[38:41]
	v_mfma_f32_16x16x32_f16 v[34:37], v[144:147], v[204:207], v[34:37]
	v_mfma_f32_16x16x32_f16 v[126:129], v[148:151], v[170:173], v[126:129]
	v_mfma_f32_16x16x32_f16 v[122:125], v[156:159], v[170:173], v[122:125]
	v_mfma_f32_16x16x32_f16 v[118:121], v[148:151], v[178:181], v[118:121]
	v_mfma_f32_16x16x32_f16 v[114:117], v[156:159], v[178:181], v[114:117]
	v_mfma_f32_16x16x32_f16 v[110:113], v[148:151], v[186:189], v[110:113]
	v_mfma_f32_16x16x32_f16 v[106:109], v[156:159], v[186:189], v[106:109]
	v_mfma_f32_16x16x32_f16 v[102:105], v[148:151], v[200:203], v[102:105]
	v_mfma_f32_16x16x32_f16 v[98:101], v[156:159], v[200:203], v[98:101]
	v_mfma_f32_16x16x32_f16 v[126:129], v[152:155], v[174:177], v[126:129]
	v_mfma_f32_16x16x32_f16 v[122:125], v[160:163], v[174:177], v[122:125]
	v_mfma_f32_16x16x32_f16 v[118:121], v[152:155], v[182:185], v[118:121]
	v_mfma_f32_16x16x32_f16 v[114:117], v[160:163], v[182:185], v[114:117]
	v_mfma_f32_16x16x32_f16 v[110:113], v[152:155], v[190:193], v[110:113]
	v_mfma_f32_16x16x32_f16 v[106:109], v[160:163], v[190:193], v[106:109]
	v_mfma_f32_16x16x32_f16 v[102:105], v[152:155], v[204:207], v[102:105]
	v_mfma_f32_16x16x32_f16 v[98:101], v[160:163], v[204:207], v[98:101]
.Lskz_1:
	s_barrier
	s_mov_b32 m0, s47
	s_nop 0
	s_add_u32 vcc_lo, s38, 0x40000
	ds_read_b128 v[170:173], v199 offset:16384
	ds_read_b128 v[174:177], v199 offset:17408
	ds_read_b128 v[178:181], v199 offset:18432
	ds_read_b128 v[182:185], v199 offset:19456
	ds_read_b128 v[186:189], v199 offset:20480
	ds_read_b128 v[190:193], v199 offset:21504
	ds_read_b128 v[200:203], v199 offset:22528
	ds_read_b128 v[204:207], v199 offset:23552
	global_load_lds_dwordx4 v0, s[38:39]
	s_nop 0
	s_mov_b32 m0, s48
	s_addc_u32 vcc_hi, s39, 0
	global_load_lds_dwordx4 v164, s[38:39]
	s_nop 0
	s_mov_b32 m0, s50
	s_nop 0
	global_load_lds_dwordx4 v0, vcc
	s_nop 0
	s_mov_b32 m0, s51
	s_nop 0
	global_load_lds_dwordx4 v164, vcc
	s_nop 0
	s_mov_b32 m0, s52
	s_nop 0
	global_load_lds_dwordx4 v0, s[42:43]
	s_mov_b32 m0, s53
	s_nop 0
	global_load_lds_dwordx4 v164, s[42:43]
	s_waitcnt vmcnt(8)
	s_waitcnt lgkmcnt(0)
	s_barrier
	s_waitcnt lgkmcnt(0)
	s_cmp_lg_u32 s101, 0
	s_cbranch_scc1 .Lskz_2
	v_mfma_f32_16x16x32_f16 v[30:33], v[132:135], v[170:173], v[30:33]
	v_mfma_f32_16x16x32_f16 v[26:29], v[140:143], v[170:173], v[26:29]
	v_mfma_f32_16x16x32_f16 v[22:25], v[132:135], v[178:181], v[22:25]
	v_mfma_f32_16x16x32_f16 v[18:21], v[140:143], v[178:181], v[18:21]
	v_mfma_f32_16x16x32_f16 v[14:17], v[132:135], v[186:189], v[14:17]
	v_mfma_f32_16x16x32_f16 v[10:13], v[140:143], v[186:189], v[10:13]
	v_mfma_f32_16x16x32_f16 v[6:9], v[132:135], v[200:203], v[6:9]
	v_mfma_f32_16x16x32_f16 v[2:5], v[140:143], v[200:203], v[2:5]
	v_mfma_f32_16x16x32_f16 v[30:33], v[136:139], v[174:177], v[30:33]
	v_mfma_f32_16x16x32_f16 v[26:29], v[144:147], v[174:177], v[26:29]
	v_mfma_f32_16x16x32_f16 v[22:25], v[136:139], v[182:185], v[22:25]
	v_mfma_f32_16x16x32_f16 v[18:21], v[144:147], v[182:185], v[18:21]
	v_mfma_f32_16x16x32_f16 v[14:17], v[136:139], v[190:193], v[14:17]
	v_mfma_f32_16x16x32_f16 v[10:13], v[144:147], v[190:193], v[10:13]
	v_mfma_f32_16x16x32_f16 v[6:9], v[136:139], v[204:207], v[6:9]
	v_mfma_f32_16x16x32_f16 v[2:5], v[144:147], v[204:207], v[2:5]
	v_mfma_f32_16x16x32_f16 v[94:97], v[148:151], v[170:173], v[94:97]
	v_mfma_f32_16x16x32_f16 v[90:93], v[156:159], v[170:173], v[90:93]
	v_mfma_f32_16x16x32_f16 v[86:89], v[148:151], v[178:181], v[86:89]
	v_mfma_f32_16x16x32_f16 v[82:85], v[156:159], v[178:181], v[82:85]
	v_mfma_f32_16x16x32_f16 v[78:81], v[148:151], v[186:189], v[78:81]
	v_mfma_f32_16x16x32_f16 v[74:77], v[156:159], v[186:189], v[74:77]
	v_mfma_f32_16x16x32_f16 v[62:65], v[148:151], v[200:203], v[62:65]
	v_mfma_f32_16x16x32_f16 v[58:61], v[156:159], v[200:203], v[58:61]
	v_mfma_f32_16x16x32_f16 v[94:97], v[152:155], v[174:177], v[94:97]
	v_mfma_f32_16x16x32_f16 v[90:93], v[160:163], v[174:177], v[90:93]
	v_mfma_f32_16x16x32_f16 v[86:89], v[152:155], v[182:185], v[86:89]
	v_mfma_f32_16x16x32_f16 v[82:85], v[160:163], v[182:185], v[82:85]
	v_mfma_f32_16x16x32_f16 v[78:81], v[152:155], v[190:193], v[78:81]
	v_mfma_f32_16x16x32_f16 v[74:77], v[160:163], v[190:193], v[74:77]
	v_mfma_f32_16x16x32_f16 v[62:65], v[152:155], v[204:207], v[62:65]
	v_mfma_f32_16x16x32_f16 v[58:61], v[160:163], v[204:207], v[58:61]
; #define PG8_STAGE(bufoff, gbase) do { _Pragma("unroll") for (int _i = 0; _i < 2; ++_i) \
;         __builtin_amdgcn_global_load_lds((const unsigned*)((const char*)(gbase) + voffA[_i]), (LAS unsigned*)(lds + (bufoff) + ldsw + _i * 8192), 16, 0, 0); } while (0)
; #define PG8_LDA(dst, b, h) do { _Pragma("unroll") for (int m = 0; m < 4; ++m) _Pragma("unroll") for (int k = 0; k < 2; ++k) dst[m][k] = *(const LAS h16x8*)(lds + PG8_SA(b, h) + aoff + m * 2048 + k * 1024); } while (0)
; #define PG8_LDB(dst, b, h) do { _Pragma("unroll") for (int n = 0; n < 2; ++n) _Pragma("unroll") for (int k = 0; k < 2; ++k) dst[n][k] = *(const LAS h16x8*)(lds + PG8_SB(b, h) + boff + n * 2048 + k * 1024); } while (0)
; #define PG8_LDA1(dst, b) do { if constexpr (!HALFM) PG8_LDA(dst, b, 1); } while (0)
; #define PG8_MMA1(At, B0, B1) do { if constexpr (!HALFM) { PG8_MMA(1, 0, At, B0); PG8_MMA(1, 1, At, B1); } } while (0)
; #define PG8_WAIT_V(n) asm volatile("s_waitcnt vmcnt(" #n ")" ::: "memory")
; #define PG8_WAIT_L(n) asm volatile("s_waitcnt lgkmcnt(" #n ")" ::: "memory")
; #define PG8_BAR __builtin_amdgcn_s_barrier()
; #define PG8_SCHED __builtin_amdgcn_sched_barrier(0)
; template <class Epi, bool ALIGN_EPI, bool SP2, bool BF = false, bool HALFM = false, class Order = StaticOrder>
; __device__ __forceinline__ void gemm_phase(LAS unsigned char* lds, const int tid, const Gemm g, const Order& S, const Epi& E, const bool dry = false) {
;     ...
;             PG8_LDB(B0, 1, 0); PG8_LDB(B1, 1, 1); PG8_SCHED; PG8_LDA(At, 1, 0); PG8_STAGE(PG8_SA(0, 1), a2 + hstep);
;             PG8_WAIT_V(8); PG8_WAIT_L(0); PG8_BAR; PG8_MMA(0, 0, At, B0); PG8_MMA(0, 1, At, B1); PG8_BAR; PG8_SCHED;
;             PG8_LDA1(At, 1); PG8_STAGE(PG8_SB(1, 0), b3); PG8_STAGE(PG8_SB(1, 1), b3 + hstep); PG8_STAGE(PG8_SA(1, 0), a3);
;             PG8_WAIT_V(8); PG8_WAIT_L(0); PG8_BAR; PG8_MMA1(At, B0, B1); PG8_BAR; PG8_SCHED;
.Lskz_2:
	s_barrier
	v_add_u32_e32 v144, s79, v198
	v_add_u32_e32 v160, s84, v198
	ds_read_b128 v[132:135], v144
	ds_read_b128 v[136:139], v144 offset:1024
	ds_read_b128 v[140:143], v144 offset:2048
	ds_read_b128 v[144:147], v144 offset:3072
	ds_read_b128 v[148:151], v160
	ds_read_b128 v[152:155], v160 offset:1024
	ds_read_b128 v[156:159], v160 offset:2048
	ds_read_b128 v[160:163], v160 offset:3072
	s_add_u32 s42, s42, 0x40000
	s_addc_u32 s43, s43, 0
	s_mov_b32 m0, s54
	s_nop 0
	ds_read_b128 v[170:173], v199 offset:32768
	ds_read_b128 v[174:177], v199 offset:33792
	ds_read_b128 v[178:181], v199 offset:34816
	ds_read_b128 v[182:185], v199 offset:35840
	ds_read_b128 v[186:189], v199 offset:36864
	ds_read_b128 v[190:193], v199 offset:37888
	ds_read_b128 v[200:203], v199 offset:38912
	ds_read_b128 v[204:207], v199 offset:39936
	global_load_lds_dwordx4 v0, s[42:43]
	s_nop 0
	s_mov_b32 m0, s55
	s_nop 0
	global_load_lds_dwordx4 v164, s[42:43]
	s_waitcnt vmcnt(8)
	s_waitcnt lgkmcnt(0)
	s_barrier
	s_waitcnt lgkmcnt(0)
	s_cmp_lg_u32 s101, 0
	s_cbranch_scc1 .Lskz_3
	v_mfma_f32_16x16x32_f16 v[70:73], v[132:135], v[170:173], v[70:73]
	v_mfma_f32_16x16x32_f16 v[66:69], v[140:143], v[170:173], v[66:69]
	v_mfma_f32_16x16x32_f16 v[50:53], v[132:135], v[178:181], v[50:53]
	v_mfma_f32_16x16x32_f16 v[46:49], v[140:143], v[178:181], v[46:49]
	v_mfma_f32_16x16x32_f16 v[54:57], v[132:135], v[186:189], v[54:57]
	v_mfma_f32_16x16x32_f16 v[42:45], v[140:143], v[186:189], v[42:45]
	v_mfma_f32_16x16x32_f16 v[38:41], v[132:135], v[200:203], v[38:41]
	v_mfma_f32_16x16x32_f16 v[34:37], v[140:143], v[200:203], v[34:37]
	v_mfma_f32_16x16x32_f16 v[70:73], v[136:139], v[174:177], v[70:73]
	v_mfma_f32_16x16x32_f16 v[66:69], v[144:147], v[174:177], v[66:69]
	v_mfma_f32_16x16x32_f16 v[50:53], v[136:139], v[182:185], v[50:53]
	v_mfma_f32_16x16x32_f16 v[46:49], v[144:147], v[182:185], v[46:49]
	v_mfma_f32_16x16x32_f16 v[54:57], v[136:139], v[190:193], v[54:57]
	v_mfma_f32_16x16x32_f16 v[42:45], v[144:147], v[190:193], v[42:45]
	v_mfma_f32_16x16x32_f16 v[38:41], v[136:139], v[204:207], v[38:41]
	v_mfma_f32_16x16x32_f16 v[34:37], v[144:147], v[204:207], v[34:37]
	v_mfma_f32_16x16x32_f16 v[126:129], v[148:151], v[170:173], v[126:129]
	v_mfma_f32_16x16x32_f16 v[122:125], v[156:159], v[170:173], v[122:125]
	v_mfma_f32_16x16x32_f16 v[118:121], v[148:151], v[178:181], v[118:121]
	v_mfma_f32_16x16x32_f16 v[114:117], v[156:159], v[178:181], v[114:117]
	v_mfma_f32_16x16x32_f16 v[110:113], v[148:151], v[186:189], v[110:113]
	v_mfma_f32_16x16x32_f16 v[106:109], v[156:159], v[186:189], v[106:109]
	v_mfma_f32_16x16x32_f16 v[102:105], v[148:151], v[200:203], v[102:105]
	v_mfma_f32_16x16x32_f16 v[98:101], v[156:159], v[200:203], v[98:101]
	v_mfma_f32_16x16x32_f16 v[126:129], v[152:155], v[174:177], v[126:129]
	v_mfma_f32_16x16x32_f16 v[122:125], v[160:163], v[174:177], v[122:125]
	v_mfma_f32_16x16x32_f16 v[118:121], v[152:155], v[182:185], v[118:121]
	v_mfma_f32_16x16x32_f16 v[114:117], v[160:163], v[182:185], v[114:117]
	v_mfma_f32_16x16x32_f16 v[110:113], v[152:155], v[190:193], v[110:113]
	v_mfma_f32_16x16x32_f16 v[106:109], v[160:163], v[190:193], v[106:109]
	v_mfma_f32_16x16x32_f16 v[102:105], v[152:155], v[204:207], v[102:105]
	v_mfma_f32_16x16x32_f16 v[98:101], v[160:163], v[204:207], v[98:101]
.Lskz_3:
	s_barrier
.Lin_seg4:
	s_mov_b32 m0, s80
	s_add_u32 vcc_lo, s38, 0x80
	s_addc_u32 vcc_hi, s39, 0
	s_add_u32 s38, s38, 0x40080
	ds_read_b128 v[170:173], v199 offset:49152
	ds_read_b128 v[174:177], v199 offset:50176
	ds_read_b128 v[178:181], v199 offset:51200
	ds_read_b128 v[182:185], v199 offset:52224
	ds_read_b128 v[186:189], v199 offset:53248
	ds_read_b128 v[190:193], v199 offset:54272
	ds_read_b128 v[200:203], v199 offset:55296
	ds_read_b128 v[204:207], v199 offset:56320
	global_load_lds_dwordx4 v0, vcc
	s_nop 0
	s_mov_b32 m0, s81
	s_addc_u32 s39, s39, 0
	global_load_lds_dwordx4 v164, vcc
	s_nop 0
	s_mov_b32 m0, s85
	s_nop 0
	global_load_lds_dwordx4 v0, s[38:39]
	s_nop 0
	s_mov_b32 m0, s86
	s_nop 0
	global_load_lds_dwordx4 v164, s[38:39]
	s_add_u32 vcc_lo, s42, 0xfffc0080
	s_addc_u32 vcc_hi, s43, -1
	s_mov_b32 m0, s82
	s_nop 0
	global_load_lds_dwordx4 v0, vcc
	s_nop 0
	s_mov_b32 m0, s83
	s_nop 0
	global_load_lds_dwordx4 v164, vcc
	s_waitcnt vmcnt(8)
	s_waitcnt lgkmcnt(0)
	s_barrier
	s_waitcnt lgkmcnt(0)
	s_cmp_lg_u32 s101, 0
	s_cbranch_scc1 .Lskz_4
	v_mfma_f32_16x16x32_f16 v[30:33], v[132:135], v[170:173], v[30:33]
	v_mfma_f32_16x16x32_f16 v[26:29], v[140:143], v[170:173], v[26:29]
	v_mfma_f32_16x16x32_f16 v[22:25], v[132:135], v[178:181], v[22:25]
	v_mfma_f32_16x16x32_f16 v[18:21], v[140:143], v[178:181], v[18:21]
	v_mfma_f32_16x16x32_f16 v[14:17], v[132:135], v[186:189], v[14:17]
	v_mfma_f32_16x16x32_f16 v[10:13], v[140:143], v[186:189], v[10:13]
	v_mfma_f32_16x16x32_f16 v[6:9], v[132:135], v[200:203], v[6:9]
	v_mfma_f32_16x16x32_f16 v[2:5], v[140:143], v[200:203], v[2:5]
	v_mfma_f32_16x16x32_f16 v[30:33], v[136:139], v[174:177], v[30:33]
	v_mfma_f32_16x16x32_f16 v[26:29], v[144:147], v[174:177], v[26:29]
	v_mfma_f32_16x16x32_f16 v[22:25], v[136:139], v[182:185], v[22:25]
	v_mfma_f32_16x16x32_f16 v[18:21], v[144:147], v[182:185], v[18:21]
	v_mfma_f32_16x16x32_f16 v[14:17], v[136:139], v[190:193], v[14:17]
	v_mfma_f32_16x16x32_f16 v[10:13], v[144:147], v[190:193], v[10:13]
	v_mfma_f32_16x16x32_f16 v[6:9], v[136:139], v[204:207], v[6:9]
	v_mfma_f32_16x16x32_f16 v[2:5], v[144:147], v[204:207], v[2:5]
	v_mfma_f32_16x16x32_f16 v[94:97], v[148:151], v[170:173], v[94:97]
	v_mfma_f32_16x16x32_f16 v[90:93], v[156:159], v[170:173], v[90:93]
	v_mfma_f32_16x16x32_f16 v[86:89], v[148:151], v[178:181], v[86:89]
	v_mfma_f32_16x16x32_f16 v[82:85], v[156:159], v[178:181], v[82:85]
	v_mfma_f32_16x16x32_f16 v[78:81], v[148:151], v[186:189], v[78:81]
	v_mfma_f32_16x16x32_f16 v[74:77], v[156:159], v[186:189], v[74:77]
	v_mfma_f32_16x16x32_f16 v[62:65], v[148:151], v[200:203], v[62:65]
	v_mfma_f32_16x16x32_f16 v[58:61], v[156:159], v[200:203], v[58:61]
	v_mfma_f32_16x16x32_f16 v[94:97], v[152:155], v[174:177], v[94:97]
	v_mfma_f32_16x16x32_f16 v[90:93], v[160:163], v[174:177], v[90:93]
	v_mfma_f32_16x16x32_f16 v[86:89], v[152:155], v[182:185], v[86:89]
	v_mfma_f32_16x16x32_f16 v[82:85], v[160:163], v[182:185], v[82:85]
	v_mfma_f32_16x16x32_f16 v[78:81], v[152:155], v[190:193], v[78:81]
	v_mfma_f32_16x16x32_f16 v[74:77], v[160:163], v[190:193], v[74:77]
	v_mfma_f32_16x16x32_f16 v[62:65], v[152:155], v[204:207], v[62:65]
	v_mfma_f32_16x16x32_f16 v[58:61], v[160:163], v[204:207], v[58:61]
.Lskz_4:
	s_barrier
	s_add_i32 s21, s21, 2
	s_add_u32 s11, s11, 0x100
	s_addc_u32 s19, s19, 0
	s_add_u32 s36, s36, 0x100
	s_addc_u32 s37, s37, 0
	s_cmp_gt_u32 s21, 13
	s_cbranch_scc0 .LBB0_561
	s_and_b64 vcc, exec, s[12:13]
	s_cbranch_vccz .LBB0_564
	s_barrier
